# v69 + gather sub-phase D with the next token's row/modulation loads double-buffered
# speedup vs baseline: 1.0025x; 1.0025x over previous
.Lgy_D_4:
	v_lshrrev_b32_e32 v142, 6, v162
	v_readlane_b32 s2, v242, 0
	v_readlane_b32 s59, v241, 24
	v_readfirstlane_b32 s29, v142
	s_lshl_b32 s2, s2, 2
	s_add_u32 s54, s2, s29
	s_load_dwordx4 s[92:95], s[0:1], 0xc0
	s_load_dwordx2 s[88:89], s[0:1], 0x120
	v_lshlrev_b32_e32 v160, 6, v168
	v_lshlrev_b32_e32 v161, 5, v168
	v_readlane_b32 s8, v240, 12
	v_readlane_b32 s9, v240, 13
	v_readlane_b32 s10, v240, 14
	v_readlane_b32 s11, v240, 15
	v_readlane_b32 s12, v240, 3
	v_readlane_b32 s13, v240, 5
	s_waitcnt lgkmcnt(0)
	s_nop 4
	global_load_dwordx4 v[80:83], v160, s[8:9] offset:0
	global_load_dwordx4 v[84:87], v160, s[8:9] offset:16
	global_load_dwordx4 v[88:91], v160, s[8:9] offset:32
	global_load_dwordx4 v[92:95], v160, s[8:9] offset:48
	global_load_dwordx4 v[96:99], v160, s[10:11] offset:0
	global_load_dwordx4 v[100:103], v160, s[10:11] offset:16
	global_load_dwordx4 v[104:107], v160, s[10:11] offset:32
	global_load_dwordx4 v[108:111], v160, s[10:11] offset:48
	s_cmp_lt_u32 s54, 0x4200
	s_cbranch_scc0 .Lgy_Ddone_12
	s_cmp_lg_u32 s12, 0
	s_cbranch_scc0 .Lgy_Dlast_13
	s_min_u32 s15, s54, 0x41ff
	s_lshl_b32 s50, s15, 12
	s_add_u32 s52, s88, s50
	s_addc_u32 s53, s89, 0
	global_load_dwordx4 v[48:51], v160, s[52:53] offset:0
	global_load_dwordx4 v[52:55], v160, s[52:53] offset:16
	global_load_dwordx4 v[56:59], v160, s[52:53] offset:32
	global_load_dwordx4 v[60:63], v160, s[52:53] offset:48
	s_cmp_lt_u32 s15, 0x2000
	s_cselect_b32 s14, 0, 1
	s_cmp_lt_u32 s15, 0x4000
	s_cselect_b32 s14, s14, 2
	s_add_u32 s16, s14, s13
	s_mul_i32 s16, s16, 0x6000
	s_add_u32 s46, s94, s16
	s_addc_u32 s47, s95, 0
	global_load_dwordx4 v[112:115], v160, s[46:47] offset:0
	global_load_dwordx4 v[116:119], v160, s[46:47] offset:16
	global_load_dwordx4 v[120:123], v160, s[46:47] offset:32
	global_load_dwordx4 v[124:127], v160, s[46:47] offset:48
	s_add_u32 s46, s46, 0x1000
	s_addc_u32 s47, s47, 0
	global_load_dwordx4 v[130:133], v160, s[46:47] offset:0
	global_load_dwordx4 v[134:137], v160, s[46:47] offset:16
	global_load_dwordx4 v[138:141], v160, s[46:47] offset:32
	global_load_dwordx4 v[142:145], v160, s[46:47] offset:48
.Lgy_Dtok_14:
	s_mov_b32 s2, s54
	s_add_u32 s99, s54, s59
	s_min_u32 s15, s99, 0x41ff
	s_lshl_b32 s50, s15, 12
	s_add_u32 s52, s88, s50
	s_addc_u32 s53, s89, 0
	global_load_dwordx4 v[0:3], v160, s[52:53] offset:0
	global_load_dwordx4 v[4:7], v160, s[52:53] offset:16
	global_load_dwordx4 v[8:11], v160, s[52:53] offset:32
	global_load_dwordx4 v[12:15], v160, s[52:53] offset:48
	s_cmp_lt_u32 s15, 0x2000
	s_cselect_b32 s14, 0, 1
	s_cmp_lt_u32 s15, 0x4000
	s_cselect_b32 s14, s14, 2
	s_add_u32 s16, s14, s13
	s_mul_i32 s16, s16, 0x6000
	s_add_u32 s46, s94, s16
	s_addc_u32 s47, s95, 0
	global_load_dwordx4 v[16:19], v160, s[46:47] offset:0
	global_load_dwordx4 v[20:23], v160, s[46:47] offset:16
	global_load_dwordx4 v[24:27], v160, s[46:47] offset:32
	global_load_dwordx4 v[28:31], v160, s[46:47] offset:48
	s_add_u32 s46, s46, 0x1000
	s_addc_u32 s47, s47, 0
	global_load_dwordx4 v[32:35], v160, s[46:47] offset:0
	global_load_dwordx4 v[36:39], v160, s[46:47] offset:16
	global_load_dwordx4 v[40:43], v160, s[46:47] offset:32
	global_load_dwordx4 v[44:47], v160, s[46:47] offset:48
	s_waitcnt vmcnt(12)
	v_add_f32_e32 v146, v48, v49
	v_add_f32_e32 v146, v146, v50
	v_add_f32_e32 v146, v146, v51
	v_add_f32_e32 v146, v146, v52
	v_add_f32_e32 v146, v146, v53
	v_add_f32_e32 v146, v146, v54
	v_add_f32_e32 v146, v146, v55
	v_add_f32_e32 v146, v146, v56
	v_add_f32_e32 v146, v146, v57
	v_add_f32_e32 v146, v146, v58
	v_add_f32_e32 v146, v146, v59
	v_add_f32_e32 v146, v146, v60
	v_add_f32_e32 v146, v146, v61
	v_add_f32_e32 v146, v146, v62
	v_add_f32_e32 v146, v146, v63
	s_nop 1
	v_add_f32_dpp v146, v146, v146 quad_perm:[1,0,3,2] row_mask:0xf bank_mask:0xf
	s_nop 1
	v_add_f32_dpp v146, v146, v146 quad_perm:[2,3,0,1] row_mask:0xf bank_mask:0xf
	s_nop 1
	v_add_f32_dpp v146, v146, v146 row_half_mirror row_mask:0xf bank_mask:0xf
	s_nop 1
	v_add_f32_dpp v146, v146, v146 row_mirror row_mask:0xf bank_mask:0xf
	s_nop 1
	v_readlane_b32 s4, v146, 0
	v_readlane_b32 s5, v146, 16
	v_readlane_b32 s6, v146, 32
	v_readlane_b32 s7, v146, 48
	s_nop 1
	v_mov_b32_e32 v147, s4
	v_add_f32_e32 v147, s5, v147
	v_add_f32_e32 v147, s6, v147
	v_add_f32_e32 v147, s7, v147
	v_mul_f32_e32 v147, 0x3a800000, v147
	v_sub_f32_e32 v48, v48, v147
	v_sub_f32_e32 v49, v49, v147
	v_sub_f32_e32 v50, v50, v147
	v_sub_f32_e32 v51, v51, v147
	v_sub_f32_e32 v52, v52, v147
	v_sub_f32_e32 v53, v53, v147
	v_sub_f32_e32 v54, v54, v147
	v_sub_f32_e32 v55, v55, v147
	v_sub_f32_e32 v56, v56, v147
	v_sub_f32_e32 v57, v57, v147
	v_sub_f32_e32 v58, v58, v147
	v_sub_f32_e32 v59, v59, v147
	v_sub_f32_e32 v60, v60, v147
	v_sub_f32_e32 v61, v61, v147
	v_sub_f32_e32 v62, v62, v147
	v_sub_f32_e32 v63, v63, v147
	v_mul_f32_e32 v146, v48, v48
	v_mul_f32_e32 v148, v49, v49
	v_add_f32_e32 v146, v146, v148
	v_mul_f32_e32 v148, v50, v50
	v_add_f32_e32 v146, v146, v148
	v_mul_f32_e32 v148, v51, v51
	v_add_f32_e32 v146, v146, v148
	v_mul_f32_e32 v148, v52, v52
	v_add_f32_e32 v146, v146, v148
	v_mul_f32_e32 v148, v53, v53
	v_add_f32_e32 v146, v146, v148
	v_mul_f32_e32 v148, v54, v54
	v_add_f32_e32 v146, v146, v148
	v_mul_f32_e32 v148, v55, v55
	v_add_f32_e32 v146, v146, v148
	v_mul_f32_e32 v148, v56, v56
	v_add_f32_e32 v146, v146, v148
	v_mul_f32_e32 v148, v57, v57
	v_add_f32_e32 v146, v146, v148
	v_mul_f32_e32 v148, v58, v58
	v_add_f32_e32 v146, v146, v148
	v_mul_f32_e32 v148, v59, v59
	v_add_f32_e32 v146, v146, v148
	v_mul_f32_e32 v148, v60, v60
	v_add_f32_e32 v146, v146, v148
	v_mul_f32_e32 v148, v61, v61
	v_add_f32_e32 v146, v146, v148
	v_mul_f32_e32 v148, v62, v62
	v_add_f32_e32 v146, v146, v148
	v_mul_f32_e32 v148, v63, v63
	v_add_f32_e32 v146, v146, v148
	s_nop 1
	v_add_f32_dpp v146, v146, v146 quad_perm:[1,0,3,2] row_mask:0xf bank_mask:0xf
	s_nop 1
	v_add_f32_dpp v146, v146, v146 quad_perm:[2,3,0,1] row_mask:0xf bank_mask:0xf
	s_nop 1
	v_add_f32_dpp v146, v146, v146 row_half_mirror row_mask:0xf bank_mask:0xf
	s_nop 1
	v_add_f32_dpp v146, v146, v146 row_mirror row_mask:0xf bank_mask:0xf
	s_nop 1
	v_readlane_b32 s4, v146, 0
	v_readlane_b32 s5, v146, 16
	v_readlane_b32 s6, v146, 32
	v_readlane_b32 s7, v146, 48
	s_nop 1
	v_mov_b32_e32 v147, s4
	v_add_f32_e32 v147, s5, v147
	v_add_f32_e32 v147, s6, v147
	v_add_f32_e32 v147, s7, v147
	v_fmamk_f32 v147, v147, 0x3a800000, v163
	s_mov_b32 s4, 0x800000
	v_cmp_gt_f32_e32 vcc, s4, v147
	v_mul_f32_e32 v148, 0x4b800000, v147
	s_nop 1
	v_cndmask_b32_e32 v147, v147, v148, vcc
	v_rsq_f32_e32 v147, v147
	s_nop 0
	v_mul_f32_e32 v148, 0x45800000, v147
	v_cndmask_b32_e32 v147, v147, v148, vcc
	v_mul_f32_e32 v48, v48, v147
	v_mul_f32_e32 v49, v49, v147
	v_mul_f32_e32 v50, v50, v147
	v_mul_f32_e32 v51, v51, v147
	v_mul_f32_e32 v52, v52, v147
	v_mul_f32_e32 v53, v53, v147
	v_mul_f32_e32 v54, v54, v147
	v_mul_f32_e32 v55, v55, v147
	v_mul_f32_e32 v56, v56, v147
	v_mul_f32_e32 v57, v57, v147
	v_mul_f32_e32 v58, v58, v147
	v_mul_f32_e32 v59, v59, v147
	v_mul_f32_e32 v60, v60, v147
	v_mul_f32_e32 v61, v61, v147
	v_mul_f32_e32 v62, v62, v147
	v_mul_f32_e32 v63, v63, v147
	v_fma_f32 v48, v80, v48, v96
	v_fma_f32 v49, v81, v49, v97
	v_fma_f32 v50, v82, v50, v98
	v_fma_f32 v51, v83, v51, v99
	v_fma_f32 v52, v84, v52, v100
	v_fma_f32 v53, v85, v53, v101
	v_fma_f32 v54, v86, v54, v102
	v_fma_f32 v55, v87, v55, v103
	v_fma_f32 v56, v88, v56, v104
	v_fma_f32 v57, v89, v57, v105
	v_fma_f32 v58, v90, v58, v106
	v_fma_f32 v59, v91, v59, v107
	v_fma_f32 v60, v92, v60, v108
	v_fma_f32 v61, v93, v61, v109
	v_fma_f32 v62, v94, v62, v110
	v_fma_f32 v63, v95, v63, v111
	s_lshl_b32 s50, s2, 12
	s_add_u32 s52, s70, s50
	s_addc_u32 s53, s71, 0
	global_store_dwordx4 v160, v[48:51], s[52:53] offset:0
	global_store_dwordx4 v160, v[52:55], s[52:53] offset:16
	global_store_dwordx4 v160, v[56:59], s[52:53] offset:32
	global_store_dwordx4 v160, v[60:63], s[52:53] offset:48
	v_add_f32_e32 v130, 1.0, v130
	v_add_f32_e32 v131, 1.0, v131
	v_add_f32_e32 v132, 1.0, v132
	v_add_f32_e32 v133, 1.0, v133
	v_add_f32_e32 v134, 1.0, v134
	v_add_f32_e32 v135, 1.0, v135
	v_add_f32_e32 v136, 1.0, v136
	v_add_f32_e32 v137, 1.0, v137
	v_add_f32_e32 v138, 1.0, v138
	v_add_f32_e32 v139, 1.0, v139
	v_add_f32_e32 v140, 1.0, v140
	v_add_f32_e32 v141, 1.0, v141
	v_add_f32_e32 v142, 1.0, v142
	v_add_f32_e32 v143, 1.0, v143
	v_add_f32_e32 v144, 1.0, v144
	v_add_f32_e32 v145, 1.0, v145
	v_fma_f32 v112, v48, v130, v112
	v_fma_f32 v113, v49, v131, v113
	v_fma_f32 v114, v50, v132, v114
	v_fma_f32 v115, v51, v133, v115
	v_fma_f32 v116, v52, v134, v116
	v_fma_f32 v117, v53, v135, v117
	v_fma_f32 v118, v54, v136, v118
	v_fma_f32 v119, v55, v137, v119
	v_fma_f32 v120, v56, v138, v120
	v_fma_f32 v121, v57, v139, v121
	v_fma_f32 v122, v58, v140, v122
	v_fma_f32 v123, v59, v141, v123
	v_fma_f32 v124, v60, v142, v124
	v_fma_f32 v125, v61, v143, v125
	v_fma_f32 v126, v62, v144, v126
	v_fma_f32 v127, v63, v145, v127
	v_cvt_pk_bf16_f32 v64, v112, v113
	v_cvt_pk_bf16_f32 v65, v114, v115
	v_cvt_pk_bf16_f32 v66, v116, v117
	v_cvt_pk_bf16_f32 v67, v118, v119
	v_cvt_pk_bf16_f32 v68, v120, v121
	v_cvt_pk_bf16_f32 v69, v122, v123
	v_cvt_pk_bf16_f32 v70, v124, v125
	v_cvt_pk_bf16_f32 v71, v126, v127
	s_lshl_b32 s50, s2, 11
	s_add_u32 s46, s74, s50
	s_addc_u32 s47, s75, 0
	global_store_dwordx4 v161, v[64:67], s[46:47]
	global_store_dwordx4 v161, v[68:71], s[46:47] offset:16
	s_nop 1
	s_mov_b32 s54, s99
	s_cmp_lt_u32 s54, 0x4200
	s_cbranch_scc0 .Lgy_Dend_15
	s_mov_b32 s2, s54
	s_add_u32 s99, s54, s59
	s_min_u32 s15, s99, 0x41ff
	s_lshl_b32 s50, s15, 12
	s_add_u32 s52, s88, s50
	s_addc_u32 s53, s89, 0
	global_load_dwordx4 v[48:51], v160, s[52:53] offset:0
	global_load_dwordx4 v[52:55], v160, s[52:53] offset:16
	global_load_dwordx4 v[56:59], v160, s[52:53] offset:32
	global_load_dwordx4 v[60:63], v160, s[52:53] offset:48
	s_cmp_lt_u32 s15, 0x2000
	s_cselect_b32 s14, 0, 1
	s_cmp_lt_u32 s15, 0x4000
	s_cselect_b32 s14, s14, 2
	s_add_u32 s16, s14, s13
	s_mul_i32 s16, s16, 0x6000
	s_add_u32 s46, s94, s16
	s_addc_u32 s47, s95, 0
	global_load_dwordx4 v[112:115], v160, s[46:47] offset:0
	global_load_dwordx4 v[116:119], v160, s[46:47] offset:16
	global_load_dwordx4 v[120:123], v160, s[46:47] offset:32
	global_load_dwordx4 v[124:127], v160, s[46:47] offset:48
	s_add_u32 s46, s46, 0x1000
	s_addc_u32 s47, s47, 0
	global_load_dwordx4 v[130:133], v160, s[46:47] offset:0
	global_load_dwordx4 v[134:137], v160, s[46:47] offset:16
	global_load_dwordx4 v[138:141], v160, s[46:47] offset:32
	global_load_dwordx4 v[142:145], v160, s[46:47] offset:48
	s_waitcnt vmcnt(12)
	v_add_f32_e32 v146, v0, v1
	v_add_f32_e32 v146, v146, v2
	v_add_f32_e32 v146, v146, v3
	v_add_f32_e32 v146, v146, v4
	v_add_f32_e32 v146, v146, v5
	v_add_f32_e32 v146, v146, v6
	v_add_f32_e32 v146, v146, v7
	v_add_f32_e32 v146, v146, v8
	v_add_f32_e32 v146, v146, v9
	v_add_f32_e32 v146, v146, v10
	v_add_f32_e32 v146, v146, v11
	v_add_f32_e32 v146, v146, v12
	v_add_f32_e32 v146, v146, v13
	v_add_f32_e32 v146, v146, v14
	v_add_f32_e32 v146, v146, v15
	s_nop 1
	v_add_f32_dpp v146, v146, v146 quad_perm:[1,0,3,2] row_mask:0xf bank_mask:0xf
	s_nop 1
	v_add_f32_dpp v146, v146, v146 quad_perm:[2,3,0,1] row_mask:0xf bank_mask:0xf
	s_nop 1
	v_add_f32_dpp v146, v146, v146 row_half_mirror row_mask:0xf bank_mask:0xf
	s_nop 1
	v_add_f32_dpp v146, v146, v146 row_mirror row_mask:0xf bank_mask:0xf
	s_nop 1
	v_readlane_b32 s4, v146, 0
	v_readlane_b32 s5, v146, 16
	v_readlane_b32 s6, v146, 32
	v_readlane_b32 s7, v146, 48
	s_nop 1
	v_mov_b32_e32 v147, s4
	v_add_f32_e32 v147, s5, v147
	v_add_f32_e32 v147, s6, v147
	v_add_f32_e32 v147, s7, v147
	v_mul_f32_e32 v147, 0x3a800000, v147
	v_sub_f32_e32 v0, v0, v147
	v_sub_f32_e32 v1, v1, v147
	v_sub_f32_e32 v2, v2, v147
	v_sub_f32_e32 v3, v3, v147
	v_sub_f32_e32 v4, v4, v147
	v_sub_f32_e32 v5, v5, v147
	v_sub_f32_e32 v6, v6, v147
	v_sub_f32_e32 v7, v7, v147
	v_sub_f32_e32 v8, v8, v147
	v_sub_f32_e32 v9, v9, v147
	v_sub_f32_e32 v10, v10, v147
	v_sub_f32_e32 v11, v11, v147
	v_sub_f32_e32 v12, v12, v147
	v_sub_f32_e32 v13, v13, v147
	v_sub_f32_e32 v14, v14, v147
	v_sub_f32_e32 v15, v15, v147
	v_mul_f32_e32 v146, v0, v0
	v_mul_f32_e32 v148, v1, v1
	v_add_f32_e32 v146, v146, v148
	v_mul_f32_e32 v148, v2, v2
	v_add_f32_e32 v146, v146, v148
	v_mul_f32_e32 v148, v3, v3
	v_add_f32_e32 v146, v146, v148
	v_mul_f32_e32 v148, v4, v4
	v_add_f32_e32 v146, v146, v148
	v_mul_f32_e32 v148, v5, v5
	v_add_f32_e32 v146, v146, v148
	v_mul_f32_e32 v148, v6, v6
	v_add_f32_e32 v146, v146, v148
	v_mul_f32_e32 v148, v7, v7
	v_add_f32_e32 v146, v146, v148
	v_mul_f32_e32 v148, v8, v8
	v_add_f32_e32 v146, v146, v148
	v_mul_f32_e32 v148, v9, v9
	v_add_f32_e32 v146, v146, v148
	v_mul_f32_e32 v148, v10, v10
	v_add_f32_e32 v146, v146, v148
	v_mul_f32_e32 v148, v11, v11
	v_add_f32_e32 v146, v146, v148
	v_mul_f32_e32 v148, v12, v12
	v_add_f32_e32 v146, v146, v148
	v_mul_f32_e32 v148, v13, v13
	v_add_f32_e32 v146, v146, v148
	v_mul_f32_e32 v148, v14, v14
	v_add_f32_e32 v146, v146, v148
	v_mul_f32_e32 v148, v15, v15
	v_add_f32_e32 v146, v146, v148
	s_nop 1
	v_add_f32_dpp v146, v146, v146 quad_perm:[1,0,3,2] row_mask:0xf bank_mask:0xf
	s_nop 1
	v_add_f32_dpp v146, v146, v146 quad_perm:[2,3,0,1] row_mask:0xf bank_mask:0xf
	s_nop 1
	v_add_f32_dpp v146, v146, v146 row_half_mirror row_mask:0xf bank_mask:0xf
	s_nop 1
	v_add_f32_dpp v146, v146, v146 row_mirror row_mask:0xf bank_mask:0xf
	s_nop 1
	v_readlane_b32 s4, v146, 0
	v_readlane_b32 s5, v146, 16
	v_readlane_b32 s6, v146, 32
	v_readlane_b32 s7, v146, 48
	s_nop 1
	v_mov_b32_e32 v147, s4
	v_add_f32_e32 v147, s5, v147
	v_add_f32_e32 v147, s6, v147
	v_add_f32_e32 v147, s7, v147
	v_fmamk_f32 v147, v147, 0x3a800000, v163
	s_mov_b32 s4, 0x800000
	v_cmp_gt_f32_e32 vcc, s4, v147
	v_mul_f32_e32 v148, 0x4b800000, v147
	s_nop 1
	v_cndmask_b32_e32 v147, v147, v148, vcc
	v_rsq_f32_e32 v147, v147
	s_nop 0
	v_mul_f32_e32 v148, 0x45800000, v147
	v_cndmask_b32_e32 v147, v147, v148, vcc
	v_mul_f32_e32 v0, v0, v147
	v_mul_f32_e32 v1, v1, v147
	v_mul_f32_e32 v2, v2, v147
	v_mul_f32_e32 v3, v3, v147
	v_mul_f32_e32 v4, v4, v147
	v_mul_f32_e32 v5, v5, v147
	v_mul_f32_e32 v6, v6, v147
	v_mul_f32_e32 v7, v7, v147
	v_mul_f32_e32 v8, v8, v147
	v_mul_f32_e32 v9, v9, v147
	v_mul_f32_e32 v10, v10, v147
	v_mul_f32_e32 v11, v11, v147
	v_mul_f32_e32 v12, v12, v147
	v_mul_f32_e32 v13, v13, v147
	v_mul_f32_e32 v14, v14, v147
	v_mul_f32_e32 v15, v15, v147
	v_fma_f32 v0, v80, v0, v96
	v_fma_f32 v1, v81, v1, v97
	v_fma_f32 v2, v82, v2, v98
	v_fma_f32 v3, v83, v3, v99
	v_fma_f32 v4, v84, v4, v100
	v_fma_f32 v5, v85, v5, v101
	v_fma_f32 v6, v86, v6, v102
	v_fma_f32 v7, v87, v7, v103
	v_fma_f32 v8, v88, v8, v104
	v_fma_f32 v9, v89, v9, v105
	v_fma_f32 v10, v90, v10, v106
	v_fma_f32 v11, v91, v11, v107
	v_fma_f32 v12, v92, v12, v108
	v_fma_f32 v13, v93, v13, v109
	v_fma_f32 v14, v94, v14, v110
	v_fma_f32 v15, v95, v15, v111
	s_lshl_b32 s50, s2, 12
	s_add_u32 s52, s70, s50
	s_addc_u32 s53, s71, 0
	global_store_dwordx4 v160, v[0:3], s[52:53] offset:0
	global_store_dwordx4 v160, v[4:7], s[52:53] offset:16
	global_store_dwordx4 v160, v[8:11], s[52:53] offset:32
	global_store_dwordx4 v160, v[12:15], s[52:53] offset:48
	v_add_f32_e32 v32, 1.0, v32
	v_add_f32_e32 v33, 1.0, v33
	v_add_f32_e32 v34, 1.0, v34
	v_add_f32_e32 v35, 1.0, v35
	v_add_f32_e32 v36, 1.0, v36
	v_add_f32_e32 v37, 1.0, v37
	v_add_f32_e32 v38, 1.0, v38
	v_add_f32_e32 v39, 1.0, v39
	v_add_f32_e32 v40, 1.0, v40
	v_add_f32_e32 v41, 1.0, v41
	v_add_f32_e32 v42, 1.0, v42
	v_add_f32_e32 v43, 1.0, v43
	v_add_f32_e32 v44, 1.0, v44
	v_add_f32_e32 v45, 1.0, v45
	v_add_f32_e32 v46, 1.0, v46
	v_add_f32_e32 v47, 1.0, v47
	v_fma_f32 v16, v0, v32, v16
	v_fma_f32 v17, v1, v33, v17
	v_fma_f32 v18, v2, v34, v18
	v_fma_f32 v19, v3, v35, v19
	v_fma_f32 v20, v4, v36, v20
	v_fma_f32 v21, v5, v37, v21
	v_fma_f32 v22, v6, v38, v22
	v_fma_f32 v23, v7, v39, v23
	v_fma_f32 v24, v8, v40, v24
	v_fma_f32 v25, v9, v41, v25
	v_fma_f32 v26, v10, v42, v26
	v_fma_f32 v27, v11, v43, v27
	v_fma_f32 v28, v12, v44, v28
	v_fma_f32 v29, v13, v45, v29
	v_fma_f32 v30, v14, v46, v30
	v_fma_f32 v31, v15, v47, v31
	v_cvt_pk_bf16_f32 v64, v16, v17
	v_cvt_pk_bf16_f32 v65, v18, v19
	v_cvt_pk_bf16_f32 v66, v20, v21
	v_cvt_pk_bf16_f32 v67, v22, v23
	v_cvt_pk_bf16_f32 v68, v24, v25
	v_cvt_pk_bf16_f32 v69, v26, v27
	v_cvt_pk_bf16_f32 v70, v28, v29
	v_cvt_pk_bf16_f32 v71, v30, v31
	s_lshl_b32 s50, s2, 11
	s_add_u32 s46, s74, s50
	s_addc_u32 s47, s75, 0
	global_store_dwordx4 v161, v[64:67], s[46:47]
	global_store_dwordx4 v161, v[68:71], s[46:47] offset:16
	s_nop 1
	s_mov_b32 s54, s99
	s_cmp_lt_u32 s54, 0x4200
	s_cbranch_scc1 .Lgy_Dtok_14

.Lgy_Dlast_13:
	s_min_u32 s15, s54, 0x41ff
	s_lshl_b32 s50, s15, 12
	s_add_u32 s52, s88, s50
	s_addc_u32 s53, s89, 0
	global_load_dwordx4 v[48:51], v160, s[52:53] offset:0
	global_load_dwordx4 v[52:55], v160, s[52:53] offset:16
	global_load_dwordx4 v[56:59], v160, s[52:53] offset:32
	global_load_dwordx4 v[60:63], v160, s[52:53] offset:48
.Lgy_Dtok_16:
	s_mov_b32 s2, s54
	s_add_u32 s99, s54, s59
	s_min_u32 s15, s99, 0x41ff
	s_lshl_b32 s50, s15, 12
	s_add_u32 s52, s88, s50
	s_addc_u32 s53, s89, 0
	global_load_dwordx4 v[0:3], v160, s[52:53] offset:0
	global_load_dwordx4 v[4:7], v160, s[52:53] offset:16
	global_load_dwordx4 v[8:11], v160, s[52:53] offset:32
	global_load_dwordx4 v[12:15], v160, s[52:53] offset:48
	s_waitcnt vmcnt(4)
	v_add_f32_e32 v146, v48, v49
	v_add_f32_e32 v146, v146, v50
	v_add_f32_e32 v146, v146, v51
	v_add_f32_e32 v146, v146, v52
	v_add_f32_e32 v146, v146, v53
	v_add_f32_e32 v146, v146, v54
	v_add_f32_e32 v146, v146, v55
	v_add_f32_e32 v146, v146, v56
	v_add_f32_e32 v146, v146, v57
	v_add_f32_e32 v146, v146, v58
	v_add_f32_e32 v146, v146, v59
	v_add_f32_e32 v146, v146, v60
	v_add_f32_e32 v146, v146, v61
	v_add_f32_e32 v146, v146, v62
	v_add_f32_e32 v146, v146, v63
	s_nop 1
	v_add_f32_dpp v146, v146, v146 quad_perm:[1,0,3,2] row_mask:0xf bank_mask:0xf
	s_nop 1
	v_add_f32_dpp v146, v146, v146 quad_perm:[2,3,0,1] row_mask:0xf bank_mask:0xf
	s_nop 1
	v_add_f32_dpp v146, v146, v146 row_half_mirror row_mask:0xf bank_mask:0xf
	s_nop 1
	v_add_f32_dpp v146, v146, v146 row_mirror row_mask:0xf bank_mask:0xf
	s_nop 1
	v_readlane_b32 s4, v146, 0
	v_readlane_b32 s5, v146, 16
	v_readlane_b32 s6, v146, 32
	v_readlane_b32 s7, v146, 48
	s_nop 1
	v_mov_b32_e32 v147, s4
	v_add_f32_e32 v147, s5, v147
	v_add_f32_e32 v147, s6, v147
	v_add_f32_e32 v147, s7, v147
	v_mul_f32_e32 v147, 0x3a800000, v147
	v_sub_f32_e32 v48, v48, v147
	v_sub_f32_e32 v49, v49, v147
	v_sub_f32_e32 v50, v50, v147
	v_sub_f32_e32 v51, v51, v147
	v_sub_f32_e32 v52, v52, v147
	v_sub_f32_e32 v53, v53, v147
	v_sub_f32_e32 v54, v54, v147
	v_sub_f32_e32 v55, v55, v147
	v_sub_f32_e32 v56, v56, v147
	v_sub_f32_e32 v57, v57, v147
	v_sub_f32_e32 v58, v58, v147
	v_sub_f32_e32 v59, v59, v147
	v_sub_f32_e32 v60, v60, v147
	v_sub_f32_e32 v61, v61, v147
	v_sub_f32_e32 v62, v62, v147
	v_sub_f32_e32 v63, v63, v147
	v_mul_f32_e32 v146, v48, v48
	v_mul_f32_e32 v148, v49, v49
	v_add_f32_e32 v146, v146, v148
	v_mul_f32_e32 v148, v50, v50
	v_add_f32_e32 v146, v146, v148
	v_mul_f32_e32 v148, v51, v51
	v_add_f32_e32 v146, v146, v148
	v_mul_f32_e32 v148, v52, v52
	v_add_f32_e32 v146, v146, v148
	v_mul_f32_e32 v148, v53, v53
	v_add_f32_e32 v146, v146, v148
	v_mul_f32_e32 v148, v54, v54
	v_add_f32_e32 v146, v146, v148
	v_mul_f32_e32 v148, v55, v55
	v_add_f32_e32 v146, v146, v148
	v_mul_f32_e32 v148, v56, v56
	v_add_f32_e32 v146, v146, v148
	v_mul_f32_e32 v148, v57, v57
	v_add_f32_e32 v146, v146, v148
	v_mul_f32_e32 v148, v58, v58
	v_add_f32_e32 v146, v146, v148
	v_mul_f32_e32 v148, v59, v59
	v_add_f32_e32 v146, v146, v148
	v_mul_f32_e32 v148, v60, v60
	v_add_f32_e32 v146, v146, v148
	v_mul_f32_e32 v148, v61, v61
	v_add_f32_e32 v146, v146, v148
	v_mul_f32_e32 v148, v62, v62
	v_add_f32_e32 v146, v146, v148
	v_mul_f32_e32 v148, v63, v63
	v_add_f32_e32 v146, v146, v148
	s_nop 1
	v_add_f32_dpp v146, v146, v146 quad_perm:[1,0,3,2] row_mask:0xf bank_mask:0xf
	s_nop 1
	v_add_f32_dpp v146, v146, v146 quad_perm:[2,3,0,1] row_mask:0xf bank_mask:0xf
	s_nop 1
	v_add_f32_dpp v146, v146, v146 row_half_mirror row_mask:0xf bank_mask:0xf
	s_nop 1
	v_add_f32_dpp v146, v146, v146 row_mirror row_mask:0xf bank_mask:0xf
	s_nop 1
	v_readlane_b32 s4, v146, 0
	v_readlane_b32 s5, v146, 16
	v_readlane_b32 s6, v146, 32
	v_readlane_b32 s7, v146, 48
	s_nop 1
	v_mov_b32_e32 v147, s4
	v_add_f32_e32 v147, s5, v147
	v_add_f32_e32 v147, s6, v147
	v_add_f32_e32 v147, s7, v147
	v_fmamk_f32 v147, v147, 0x3a800000, v163
	s_mov_b32 s4, 0x800000
	v_cmp_gt_f32_e32 vcc, s4, v147
	v_mul_f32_e32 v148, 0x4b800000, v147
	s_nop 1
	v_cndmask_b32_e32 v147, v147, v148, vcc
	v_rsq_f32_e32 v147, v147
	s_nop 0
	v_mul_f32_e32 v148, 0x45800000, v147
	v_cndmask_b32_e32 v147, v147, v148, vcc
	v_mul_f32_e32 v48, v48, v147
	v_mul_f32_e32 v49, v49, v147
	v_mul_f32_e32 v50, v50, v147
	v_mul_f32_e32 v51, v51, v147
	v_mul_f32_e32 v52, v52, v147
	v_mul_f32_e32 v53, v53, v147
	v_mul_f32_e32 v54, v54, v147
	v_mul_f32_e32 v55, v55, v147
	v_mul_f32_e32 v56, v56, v147
	v_mul_f32_e32 v57, v57, v147
	v_mul_f32_e32 v58, v58, v147
	v_mul_f32_e32 v59, v59, v147
	v_mul_f32_e32 v60, v60, v147
	v_mul_f32_e32 v61, v61, v147
	v_mul_f32_e32 v62, v62, v147
	v_mul_f32_e32 v63, v63, v147
	v_fma_f32 v48, v80, v48, v96
	v_fma_f32 v49, v81, v49, v97
	v_fma_f32 v50, v82, v50, v98
	v_fma_f32 v51, v83, v51, v99
	v_fma_f32 v52, v84, v52, v100
	v_fma_f32 v53, v85, v53, v101
	v_fma_f32 v54, v86, v54, v102
	v_fma_f32 v55, v87, v55, v103
	v_fma_f32 v56, v88, v56, v104
	v_fma_f32 v57, v89, v57, v105
	v_fma_f32 v58, v90, v58, v106
	v_fma_f32 v59, v91, v59, v107
	v_fma_f32 v60, v92, v60, v108
	v_fma_f32 v61, v93, v61, v109
	v_fma_f32 v62, v94, v62, v110
	v_fma_f32 v63, v95, v63, v111
	s_lshl_b32 s50, s2, 12
	s_cmp_lt_u32 s2, 0x4000
	s_cbranch_scc0 .Lgy_stdone_18
	s_add_u32 s46, s92, s50
	s_addc_u32 s47, s93, 0
	global_store_dwordx4 v160, v[48:51], s[46:47] offset:0
	global_store_dwordx4 v160, v[52:55], s[46:47] offset:16
	global_store_dwordx4 v160, v[56:59], s[46:47] offset:32
	global_store_dwordx4 v160, v[60:63], s[46:47] offset:48
.Lgy_stdone_18:
	s_nop 1
	s_mov_b32 s54, s99
	s_cmp_lt_u32 s54, 0x4200
	s_cbranch_scc0 .Lgy_Dend_17
	s_mov_b32 s2, s54
	s_add_u32 s99, s54, s59
	s_min_u32 s15, s99, 0x41ff
	s_lshl_b32 s50, s15, 12
	s_add_u32 s52, s88, s50
	s_addc_u32 s53, s89, 0
	global_load_dwordx4 v[48:51], v160, s[52:53] offset:0
	global_load_dwordx4 v[52:55], v160, s[52:53] offset:16
	global_load_dwordx4 v[56:59], v160, s[52:53] offset:32
	global_load_dwordx4 v[60:63], v160, s[52:53] offset:48
	s_waitcnt vmcnt(4)
	v_add_f32_e32 v146, v0, v1
	v_add_f32_e32 v146, v146, v2
	v_add_f32_e32 v146, v146, v3
	v_add_f32_e32 v146, v146, v4
	v_add_f32_e32 v146, v146, v5
	v_add_f32_e32 v146, v146, v6
	v_add_f32_e32 v146, v146, v7
	v_add_f32_e32 v146, v146, v8
	v_add_f32_e32 v146, v146, v9
	v_add_f32_e32 v146, v146, v10
	v_add_f32_e32 v146, v146, v11
	v_add_f32_e32 v146, v146, v12
	v_add_f32_e32 v146, v146, v13
	v_add_f32_e32 v146, v146, v14
	v_add_f32_e32 v146, v146, v15
	s_nop 1
	v_add_f32_dpp v146, v146, v146 quad_perm:[1,0,3,2] row_mask:0xf bank_mask:0xf
	s_nop 1
	v_add_f32_dpp v146, v146, v146 quad_perm:[2,3,0,1] row_mask:0xf bank_mask:0xf
	s_nop 1
	v_add_f32_dpp v146, v146, v146 row_half_mirror row_mask:0xf bank_mask:0xf
	s_nop 1
	v_add_f32_dpp v146, v146, v146 row_mirror row_mask:0xf bank_mask:0xf
	s_nop 1
	v_readlane_b32 s4, v146, 0
	v_readlane_b32 s5, v146, 16
	v_readlane_b32 s6, v146, 32
	v_readlane_b32 s7, v146, 48
	s_nop 1
	v_mov_b32_e32 v147, s4
	v_add_f32_e32 v147, s5, v147
	v_add_f32_e32 v147, s6, v147
	v_add_f32_e32 v147, s7, v147
	v_mul_f32_e32 v147, 0x3a800000, v147
	v_sub_f32_e32 v0, v0, v147
	v_sub_f32_e32 v1, v1, v147
	v_sub_f32_e32 v2, v2, v147
	v_sub_f32_e32 v3, v3, v147
	v_sub_f32_e32 v4, v4, v147
	v_sub_f32_e32 v5, v5, v147
	v_sub_f32_e32 v6, v6, v147
	v_sub_f32_e32 v7, v7, v147
	v_sub_f32_e32 v8, v8, v147
	v_sub_f32_e32 v9, v9, v147
	v_sub_f32_e32 v10, v10, v147
	v_sub_f32_e32 v11, v11, v147
	v_sub_f32_e32 v12, v12, v147
	v_sub_f32_e32 v13, v13, v147
	v_sub_f32_e32 v14, v14, v147
	v_sub_f32_e32 v15, v15, v147
	v_mul_f32_e32 v146, v0, v0
	v_mul_f32_e32 v148, v1, v1
	v_add_f32_e32 v146, v146, v148
	v_mul_f32_e32 v148, v2, v2
	v_add_f32_e32 v146, v146, v148
	v_mul_f32_e32 v148, v3, v3
	v_add_f32_e32 v146, v146, v148
	v_mul_f32_e32 v148, v4, v4
	v_add_f32_e32 v146, v146, v148
	v_mul_f32_e32 v148, v5, v5
	v_add_f32_e32 v146, v146, v148
	v_mul_f32_e32 v148, v6, v6
	v_add_f32_e32 v146, v146, v148
	v_mul_f32_e32 v148, v7, v7
	v_add_f32_e32 v146, v146, v148
	v_mul_f32_e32 v148, v8, v8
	v_add_f32_e32 v146, v146, v148
	v_mul_f32_e32 v148, v9, v9
	v_add_f32_e32 v146, v146, v148
	v_mul_f32_e32 v148, v10, v10
	v_add_f32_e32 v146, v146, v148
	v_mul_f32_e32 v148, v11, v11
	v_add_f32_e32 v146, v146, v148
	v_mul_f32_e32 v148, v12, v12
	v_add_f32_e32 v146, v146, v148
	v_mul_f32_e32 v148, v13, v13
	v_add_f32_e32 v146, v146, v148
	v_mul_f32_e32 v148, v14, v14
	v_add_f32_e32 v146, v146, v148
	v_mul_f32_e32 v148, v15, v15
	v_add_f32_e32 v146, v146, v148
	s_nop 1
	v_add_f32_dpp v146, v146, v146 quad_perm:[1,0,3,2] row_mask:0xf bank_mask:0xf
	s_nop 1
	v_add_f32_dpp v146, v146, v146 quad_perm:[2,3,0,1] row_mask:0xf bank_mask:0xf
	s_nop 1
	v_add_f32_dpp v146, v146, v146 row_half_mirror row_mask:0xf bank_mask:0xf
	s_nop 1
	v_add_f32_dpp v146, v146, v146 row_mirror row_mask:0xf bank_mask:0xf
	s_nop 1
	v_readlane_b32 s4, v146, 0
	v_readlane_b32 s5, v146, 16
	v_readlane_b32 s6, v146, 32
	v_readlane_b32 s7, v146, 48
	s_nop 1
	v_mov_b32_e32 v147, s4
	v_add_f32_e32 v147, s5, v147
	v_add_f32_e32 v147, s6, v147
	v_add_f32_e32 v147, s7, v147
	v_fmamk_f32 v147, v147, 0x3a800000, v163
	s_mov_b32 s4, 0x800000
	v_cmp_gt_f32_e32 vcc, s4, v147
	v_mul_f32_e32 v148, 0x4b800000, v147
	s_nop 1
	v_cndmask_b32_e32 v147, v147, v148, vcc
	v_rsq_f32_e32 v147, v147
	s_nop 0
	v_mul_f32_e32 v148, 0x45800000, v147
	v_cndmask_b32_e32 v147, v147, v148, vcc
	v_mul_f32_e32 v0, v0, v147
	v_mul_f32_e32 v1, v1, v147
	v_mul_f32_e32 v2, v2, v147
	v_mul_f32_e32 v3, v3, v147
	v_mul_f32_e32 v4, v4, v147
	v_mul_f32_e32 v5, v5, v147
	v_mul_f32_e32 v6, v6, v147
	v_mul_f32_e32 v7, v7, v147
	v_mul_f32_e32 v8, v8, v147
	v_mul_f32_e32 v9, v9, v147
	v_mul_f32_e32 v10, v10, v147
	v_mul_f32_e32 v11, v11, v147
	v_mul_f32_e32 v12, v12, v147
	v_mul_f32_e32 v13, v13, v147
	v_mul_f32_e32 v14, v14, v147
	v_mul_f32_e32 v15, v15, v147
	v_fma_f32 v0, v80, v0, v96
	v_fma_f32 v1, v81, v1, v97
	v_fma_f32 v2, v82, v2, v98
	v_fma_f32 v3, v83, v3, v99
	v_fma_f32 v4, v84, v4, v100
	v_fma_f32 v5, v85, v5, v101
	v_fma_f32 v6, v86, v6, v102
	v_fma_f32 v7, v87, v7, v103
	v_fma_f32 v8, v88, v8, v104
	v_fma_f32 v9, v89, v9, v105
	v_fma_f32 v10, v90, v10, v106
	v_fma_f32 v11, v91, v11, v107
	v_fma_f32 v12, v92, v12, v108
	v_fma_f32 v13, v93, v13, v109
	v_fma_f32 v14, v94, v14, v110
	v_fma_f32 v15, v95, v15, v111
	s_lshl_b32 s50, s2, 12
	s_cmp_lt_u32 s2, 0x4000
	s_cbranch_scc0 .Lgy_stdone_19
	s_add_u32 s46, s92, s50
	s_addc_u32 s47, s93, 0
	global_store_dwordx4 v160, v[0:3], s[46:47] offset:0
	global_store_dwordx4 v160, v[4:7], s[46:47] offset:16
	global_store_dwordx4 v160, v[8:11], s[46:47] offset:32
	global_store_dwordx4 v160, v[12:15], s[46:47] offset:48
.Lgy_stdone_19:
	s_nop 1
	s_mov_b32 s54, s99
	s_cmp_lt_u32 s54, 0x4200
	s_cbranch_scc1 .Lgy_Dtok_16
.Lgy_Dend_17:
	s_branch .Lgy_Ddone_12
.Lgy_Ddone_12:
.Lgy_exit_5:
	s_waitcnt vmcnt(0) lgkmcnt(0)
	s_mov_b64 exec, -1
	s_mov_b64 s[30:31], -1
	s_branch .LBB1_48
